# baseline (speedup 1.0000x reference)
; #define NEG_INF (-__builtin_inff())
; DI int pi_row(int r) { return (r & ~12) | ((r & 4) << 1) | ((r & 8) >> 1); }
; DI void state_init(AState& st) {
;   st.m = NEG_INF; st.l = 0.f;
; #pragma unroll
;   for (int i = 0; i < 16; ++i) { st.o0[i] = 0.f; st.o1[i] = 0.f; }
; }
; DI void nsa_group(const u16* R, const u16* T, const float* Oc, const float* Ow, const u32* selm, const float* bg, const float* gh, u16* obuf, int qtile, char* lds) {
;     ...
;         const char* b = lds + buf * (2 * NG_TB) + part * NG_TB;
;         const u16* sK = reinterpret_cast<const u16*>(b);
;         const u16* sV = reinterpret_cast<const u16*>(b + 32 * FG_KROW * 2);
;         KV kv;
;         const int prow = pi_row(r);
; #pragma unroll
;         for (int ks = 0; ks < 4; ++ks) kv.k[ks] = ld16(sK + prow * FG_KROW + ks * 16 + h2 * 8);
; #pragma unroll
;         for (int dt = 0; dt < 2; ++dt)
; #pragma unroll
;           for (int a = 0; a < 2; ++a) kv.v[dt * 2 + a] = ld16(sV + (dt * 32 + r) * FG_VROW + a * 16 + h2 * 8);
;         f32x16 s = qk_tile(kv, q);
;         float sc[16];
;         const int nb = myn + 8 * h2;
; #pragma unroll
;         for (int i = 0; i < 16; ++i) {
;           const int n = nb + (i & 7) + 16 * (i >> 3);
;           const int dist = tq - n;
;           sc[i] = (dist >= 0 && mylb) ? s[i] + nslope * (float)dist : NEG_INF;
.LBB0_1145:
	s_or_b64 exec, exec, s[46:47]
	s_lshl_b32 s11, s73, 1
	s_or_b32 s11, s11, 1
	v_cvt_f32_ubyte0_e32 v0, s11
	s_mov_b32 s11, 0x42fc0000
	v_cmp_lt_f32_e32 vcc, s11, v0
	s_and_b64 s[46:47], vcc, exec
	s_cselect_b32 s14, 0xffffffc0, 0
	v_cndmask_b32_e32 v2, 0, v187, vcc
	v_sub_f32_e32 v0, v2, v0
	v_exp_f32_e32 v0, v0
	v_lshlrev_b32_e32 v2, 1, v4
	v_lshrrev_b32_e32 v3, 1, v95
	v_and_b32_e32 v2, 8, v2
	v_ldexp_f32 v109, v0, s14
	v_and_b32_e32 v0, 19, v95
	v_and_b32_e32 v3, 4, v3
	v_or3_b32 v0, v0, v2, v3
	v_mov_b32_e32 v14, v1
	v_mov_b32_e32 v15, v1
	s_cmpk_lt_u32 s79, 0x100
	s_mul_i32 s14, s81, 0x2600
	v_mul_u32_u24_e32 v110, 0x90, v0
	v_mul_u32_u24_e32 v113, 0x50, v4
	v_mov_b32_e32 v0, v1
	v_mov_b32_e32 v2, v1
	v_mov_b32_e32 v3, v1
	v_mov_b32_e32 v4, v1
	v_mov_b32_e32 v5, v1
	v_mov_b32_e32 v6, v1
	v_mov_b32_e32 v7, v1
	v_mov_b32_e32 v8, v1
	v_mov_b32_e32 v9, v1
	v_mov_b32_e32 v10, v1
	v_mov_b32_e32 v11, v1
	v_mov_b32_e32 v12, v1
	v_mov_b32_e32 v13, v1
	v_mov_b64_e32 v[46:47], v[14:15]
	v_mov_b64_e32 v[30:31], v[14:15]
	s_mov_b32 s11, 0
	s_cselect_b64 s[46:47], -1, 0
	s_add_i32 s86, s14, 16
	v_lshlrev_b32_e32 v111, 4, v105
	v_lshlrev_b32_e32 v112, 3, v105
	v_add_u32_e32 v114, -2, v88
	v_add_u32_e32 v115, -3, v88
	v_add_u32_e32 v116, -4, v88
	v_add_u32_e32 v117, -5, v88
	v_add_u32_e32 v118, -6, v88
	v_add_u32_e32 v119, -7, v88
	v_add_u32_e32 v120, -16, v88
	v_subrev_u32_e32 v121, 17, v88
	v_subrev_u32_e32 v122, 18, v88
	v_subrev_u32_e32 v123, 19, v88
	v_subrev_u32_e32 v124, 20, v88
	v_subrev_u32_e32 v125, 21, v88
	v_subrev_u32_e32 v126, 22, v88
	v_subrev_u32_e32 v127, 23, v88
	v_mov_b32_e32 v94, 0
	v_mov_b32_e32 v128, 0xff800000
	v_mov_b64_e32 v[44:45], v[12:13]
	v_mov_b64_e32 v[42:43], v[10:11]
	v_mov_b64_e32 v[40:41], v[8:9]
	v_mov_b64_e32 v[38:39], v[6:7]
	v_mov_b64_e32 v[36:37], v[4:5]
	v_mov_b64_e32 v[34:35], v[2:3]
	v_mov_b64_e32 v[32:33], v[0:1]
	v_mov_b64_e32 v[28:29], v[12:13]
	v_mov_b64_e32 v[26:27], v[10:11]
	v_mov_b64_e32 v[24:25], v[8:9]
	v_mov_b64_e32 v[22:23], v[6:7]
	v_mov_b64_e32 v[20:21], v[4:5]
	v_mov_b64_e32 v[18:19], v[2:3]
	v_mov_b64_e32 v[16:17], v[0:1]
	s_waitcnt vmcnt(0) lgkmcnt(0)
	s_barrier

; #define NEG_INF (-__builtin_inff())
; DI int pi_row(int r) { return (r & ~12) | ((r & 4) << 1) | ((r & 8) >> 1); }
; DI void softmax_step(float (&sc)[16], AState& st, const KV& kv) {
;   float mx = NEG_INF;
; #pragma unroll
;   for (int i = 0; i < 16; ++i) mx = fmaxf(mx, sc[i]);
;   mx = fmaxf(mx, __shfl_xor(mx, 32));
;   const float mnew = fmaxf(st.m, mx);
;   const float meff = (mnew == NEG_INF) ? 0.f : mnew;
;   const float alpha = __expf(st.m - meff);
;   float rs = 0.f;
; #pragma unroll
;   for (int i = 0; i < 16; ++i) { sc[i] = __expf(sc[i] - meff); rs += sc[i]; }
;   st.l = st.l * alpha + rs;
;   st.m = mnew;
;   if (__any(alpha != 1.f)) {
; #pragma unroll
;     for (int i = 0; i < 16; ++i) { st.o0[i] *= alpha; st.o1[i] *= alpha; }
; DI void nsa_group(const u16* R, const u16* T, const float* Oc, const float* Ow, const u32* selm, const float* bg, const float* gh, u16* obuf, int qtile, char* lds) {
;     ...
;         const char* b = lds + buf * (2 * NG_TB) + part * NG_TB;
;         const u16* sK = reinterpret_cast<const u16*>(b);
;         const u16* sV = reinterpret_cast<const u16*>(b + 32 * FG_KROW * 2);
;         KV kv;
;         const int prow = pi_row(r);
; #pragma unroll
;         for (int ks = 0; ks < 4; ++ks) kv.k[ks] = ld16(sK + prow * FG_KROW + ks * 16 + h2 * 8);
; #pragma unroll
;         for (int dt = 0; dt < 2; ++dt)
; #pragma unroll
;           for (int a = 0; a < 2; ++a) kv.v[dt * 2 + a] = ld16(sV + (dt * 32 + r) * FG_VROW + a * 16 + h2 * 8);
;         f32x16 s = qk_tile(kv, q);
;         float sc[16];
;         const int nb = myn + 8 * h2;
; #pragma unroll
;         for (int i = 0; i < 16; ++i) {
;           const int n = nb + (i & 7) + 16 * (i >> 3);
;           const int dist = tq - n;
;           sc[i] = (dist >= 0 && mylb) ? s[i] + nslope * (float)dist : NEG_INF;
;         }
;         softmax_step(sc, st, kv);
.LBB0_1189:
	s_or_b64 exec, exec, s[54:55]
	s_or_b64 s[52:53], s[46:47], s[52:53]
	s_andn2_b64 vcc, exec, s[52:53]
	s_cbranch_vccnz .LBB0_1193
	s_and_b64 s[52:53], s[46:47], exec
	s_mul_i32 s14, s11, 0x4c00
	s_cselect_b32 s12, s12, s91
	s_add_i32 s14, s86, s14
	v_add_u32_e32 v0, s14, v111
	v_add_u32_e32 v10, v0, v110
	ds_read_b128 v[2:5], v10
	ds_read_b128 v[6:9], v10 offset:32
	v_cndmask_b32_e64 v11, 0, 1, s[48:49]
	v_cndmask_b32_e64 v12, 0, 1, s[50:51]
	s_waitcnt lgkmcnt(1)
	v_mfma_f32_32x32x16_bf16 v[48:63], v[2:5], v[64:67], 0
	v_cndmask_b32_e64 v2, v12, v11, s[46:47]
	v_and_b32_e32 v2, 1, v2
	v_cmp_eq_u32_e32 vcc, 1, v2
	ds_read_b128 v[2:5], v10 offset:64
	v_add_u32_e32 v11, s12, v112
	v_sub_u32_e32 v12, v88, v11
	v_xad_u32 v13, v11, -1, v88
	s_waitcnt lgkmcnt(1)
	v_mfma_f32_32x32x16_bf16 v[48:63], v[6:9], v[68:71], v[48:63]
	ds_read_b128 v[6:9], v10 offset:96
	v_cvt_f32_u32_e32 v10, v12
	v_sub_u32_e32 v14, v114, v11
	v_sub_u32_e32 v15, v115, v11
	v_cmp_lt_i32_e64 s[48:49], -1, v12
	v_cmp_lt_i32_e64 s[50:51], -1, v13
	s_and_b64 s[48:49], s[48:49], vcc
	s_waitcnt lgkmcnt(1)
	v_mfma_f32_32x32x16_bf16 v[48:63], v[2:5], v[72:75], v[48:63]
	v_cvt_f32_u32_e32 v2, v13
	v_cvt_f32_u32_e32 v3, v14
	v_cvt_f32_u32_e32 v4, v15
	v_sub_u32_e32 v129, v116, v11
	v_cmp_lt_i32_e64 s[52:53], -1, v14
	v_cmp_lt_i32_e64 s[54:55], -1, v15
	v_cvt_f32_u32_e32 v5, v129
	s_waitcnt lgkmcnt(0)
	v_mfma_f32_32x32x16_bf16 v[48:63], v[6:9], v[76:79], v[48:63]
	v_cmp_lt_i32_e64 s[56:57], -1, v129
	s_nop 10
	v_fma_f32 v6, -v109, v10, v48
	v_fma_f32 v2, -v109, v2, v49
	v_cndmask_b32_e64 v130, v184, v6, s[48:49]
	s_and_b64 s[48:49], s[50:51], vcc
	v_fma_f32 v3, -v109, v3, v50
	v_cndmask_b32_e64 v15, v184, v2, s[48:49]
	s_and_b64 s[48:49], s[52:53], vcc
	v_fma_f32 v4, -v109, v4, v51
	v_cndmask_b32_e64 v14, v184, v3, s[48:49]
	s_and_b64 s[48:49], s[54:55], vcc
	v_sub_u32_e32 v3, v117, v11
	v_cndmask_b32_e64 v131, v184, v4, s[48:49]
	v_cvt_f32_u32_e32 v4, v3
	v_fma_f32 v2, -v109, v5, v52
	s_and_b64 s[48:49], s[56:57], vcc
	v_cndmask_b32_e64 v52, v184, v2, s[48:49]
	v_cmp_lt_i32_e64 s[48:49], -1, v3
	v_sub_u32_e32 v3, v118, v11
	v_fma_f32 v2, -v109, v4, v53
	v_cvt_f32_u32_e32 v4, v3
	s_and_b64 s[48:49], s[48:49], vcc
	v_cndmask_b32_e64 v53, v184, v2, s[48:49]
	v_cmp_lt_i32_e64 s[48:49], -1, v3
	v_sub_u32_e32 v3, v119, v11
	v_fma_f32 v2, -v109, v4, v54
	v_cvt_f32_u32_e32 v4, v3
	s_and_b64 s[48:49], s[48:49], vcc
	v_cndmask_b32_e64 v54, v184, v2, s[48:49]
	v_cmp_lt_i32_e64 s[48:49], -1, v3
	v_sub_u32_e32 v3, v120, v11
	v_fma_f32 v2, -v109, v4, v55
	v_cvt_f32_u32_e32 v4, v3
	s_and_b64 s[48:49], s[48:49], vcc
	v_cndmask_b32_e64 v55, v184, v2, s[48:49]
	v_cmp_lt_i32_e64 s[48:49], -1, v3
	v_sub_u32_e32 v3, v121, v11
	v_fma_f32 v2, -v109, v4, v56
	v_cvt_f32_u32_e32 v4, v3
	s_and_b64 s[48:49], s[48:49], vcc
	v_cndmask_b32_e64 v56, v184, v2, s[48:49]
	v_cmp_lt_i32_e64 s[48:49], -1, v3
	v_sub_u32_e32 v3, v122, v11
	v_fma_f32 v2, -v109, v4, v57
	v_cvt_f32_u32_e32 v4, v3
	s_and_b64 s[48:49], s[48:49], vcc
	v_cndmask_b32_e64 v57, v184, v2, s[48:49]
	v_cmp_lt_i32_e64 s[48:49], -1, v3
	v_sub_u32_e32 v3, v123, v11
	v_fma_f32 v2, -v109, v4, v58
	v_cvt_f32_u32_e32 v4, v3
	s_and_b64 s[48:49], s[48:49], vcc
	v_cndmask_b32_e64 v132, v184, v2, s[48:49]
	v_cmp_lt_i32_e64 s[48:49], -1, v3
	v_sub_u32_e32 v3, v124, v11
	v_fma_f32 v2, -v109, v4, v59
	v_cvt_f32_u32_e32 v4, v3
	s_and_b64 s[48:49], s[48:49], vcc
	v_cndmask_b32_e64 v59, v184, v2, s[48:49]
	v_cmp_lt_i32_e64 s[48:49], -1, v3
	v_sub_u32_e32 v3, v125, v11
	v_fma_f32 v2, -v109, v4, v60
	v_cvt_f32_u32_e32 v4, v3
	s_and_b64 s[48:49], s[48:49], vcc
	v_cndmask_b32_e64 v60, v184, v2, s[48:49]
	v_cmp_lt_i32_e64 s[48:49], -1, v3
	v_sub_u32_e32 v3, v126, v11
	v_fma_f32 v2, -v109, v4, v61
	v_cvt_f32_u32_e32 v4, v3
	s_and_b64 s[48:49], s[48:49], vcc
	v_cndmask_b32_e64 v133, v184, v2, s[48:49]
	v_cmp_lt_i32_e64 s[48:49], -1, v3
	v_sub_u32_e32 v3, v127, v11
	v_fma_f32 v2, -v109, v4, v62
	v_cvt_f32_u32_e32 v4, v3
	s_and_b64 s[48:49], s[48:49], vcc
	v_cndmask_b32_e64 v62, v184, v2, s[48:49]
	v_cmp_lt_i32_e64 s[48:49], -1, v3
	v_fma_f32 v2, -v109, v4, v63
	s_and_b64 vcc, s[48:49], vcc
	v_cndmask_b32_e32 v58, v184, v2, vcc
	v_max3_f32 v2, v130, s35, v15
	v_max3_f32 v2, v2, v14, v131
	v_max3_f32 v2, v2, v52, v53
	v_max3_f32 v2, v2, v54, v55
	v_max3_f32 v2, v2, v56, v57
	v_max3_f32 v2, v2, v132, v59
	v_max3_f32 v2, v2, v60, v133
	v_max3_f32 v2, v2, v62, v58
	ds_bpermute_b32 v3, v138, v2
	v_add_u32_e32 v4, v0, v113
	ds_read_b128 v[48:51], v4 offset:4608
	ds_read_b128 v[10:13], v4 offset:4640
	s_waitcnt lgkmcnt(2)
	v_max3_f32 v129, v128, v2, v3
	v_cmp_neq_f32_e32 vcc, s35, v129
	ds_read_b128 v[6:9], v4 offset:7168
	ds_read_b128 v[2:5], v4 offset:7200
	v_cndmask_b32_e32 v61, 0, v129, vcc
	v_sub_f32_e32 v0, v128, v61
	v_mul_f32_e32 v0, 0x3fb8aa3b, v0
	v_exp_f32_e32 v0, v0
	s_nop 0
	v_cmp_neq_f32_e32 vcc, 1.0, v0
	s_cbranch_vccz .LBB0_1192
	v_pk_mul_f32 v[46:47], v[46:47], v[0:1] op_sel_hi:[1,0]
	v_pk_mul_f32 v[44:45], v[44:45], v[0:1] op_sel_hi:[1,0]
	v_pk_mul_f32 v[42:43], v[42:43], v[0:1] op_sel_hi:[1,0]
	v_pk_mul_f32 v[40:41], v[40:41], v[0:1] op_sel_hi:[1,0]
	v_pk_mul_f32 v[38:39], v[38:39], v[0:1] op_sel_hi:[1,0]
	v_pk_mul_f32 v[36:37], v[36:37], v[0:1] op_sel_hi:[1,0]
	v_pk_mul_f32 v[34:35], v[34:35], v[0:1] op_sel_hi:[1,0]
	v_pk_mul_f32 v[32:33], v[32:33], v[0:1] op_sel_hi:[1,0]
	v_pk_mul_f32 v[30:31], v[30:31], v[0:1] op_sel_hi:[1,0]
	v_pk_mul_f32 v[28:29], v[28:29], v[0:1] op_sel_hi:[1,0]
	v_pk_mul_f32 v[26:27], v[26:27], v[0:1] op_sel_hi:[1,0]
	v_pk_mul_f32 v[24:25], v[24:25], v[0:1] op_sel_hi:[1,0]
	v_pk_mul_f32 v[22:23], v[22:23], v[0:1] op_sel_hi:[1,0]
	v_pk_mul_f32 v[20:21], v[20:21], v[0:1] op_sel_hi:[1,0]
	v_pk_mul_f32 v[18:19], v[18:19], v[0:1] op_sel_hi:[1,0]
	v_pk_mul_f32 v[16:17], v[16:17], v[0:1] op_sel_hi:[1,0]
